# gla main stage (c): three decay-vector LDS reads hoisted; gemm_in K-loop: per-phase s_setprio flips removed (static-priority lever tested: no raise was best)
# speedup vs baseline: 1.0048x; 1.0048x over previous
.LBB0_362:
	v_add_u32_e32 v144, s77, v137
	ds_read_b128 v[146:149], v144
	ds_read_b128 v[150:153], v144 offset:1024
	ds_read_b128 v[154:157], v144 offset:2048
	ds_read_b128 v[158:161], v144 offset:3072
	s_add_u32 s49, s36, s38
	s_addc_u32 s52, s37, s39
	s_add_u32 s50, s49, 0x80
	s_addc_u32 s51, s52, 0
	v_add_u32_e32 v144, 0xc000, v131
	v_lshl_add_u64 v[190:191], s[50:51], 0, v[192:193]
	v_readfirstlane_b32 s50, v144
	v_add_u32_e32 v145, 0xe000, v131
	s_mov_b32 m0, s50
	v_readfirstlane_b32 s50, v145
	ds_read_b128 v[162:165], v128
	ds_read_b128 v[166:169], v128 offset:1024
	ds_read_b128 v[170:173], v128 offset:2048
	ds_read_b128 v[174:177], v128 offset:3072
	ds_read_b128 v[178:181], v128 offset:4096
	ds_read_b128 v[182:185], v128 offset:5120
	ds_read_b128 v[186:189], v128 offset:6144
	ds_read_b128 v[196:199], v128 offset:7168
	global_load_lds_dwordx4 v[190:191], off
	v_lshl_add_u64 v[190:191], v[190:191], 0, s[4:5]
	s_mov_b32 m0, s50
	s_nop 0
	global_load_lds_dwordx4 v[190:191], off
	s_waitcnt lgkmcnt(8)
	s_barrier
	s_waitcnt lgkmcnt(0)
	s_waitcnt lgkmcnt(0)
	v_mfma_f32_16x16x32_bf16 v[124:127], v[162:165], v[146:149], v[124:127]
	v_mfma_f32_16x16x32_bf16 v[120:123], v[162:165], v[154:157], v[120:123]
	v_mfma_f32_16x16x32_bf16 v[116:119], v[170:173], v[146:149], v[116:119]
	v_mfma_f32_16x16x32_bf16 v[112:115], v[170:173], v[154:157], v[112:115]
	v_mfma_f32_16x16x32_bf16 v[108:111], v[178:181], v[146:149], v[108:111]
	v_mfma_f32_16x16x32_bf16 v[104:107], v[178:181], v[154:157], v[104:107]
	v_mfma_f32_16x16x32_bf16 v[100:103], v[186:189], v[146:149], v[100:103]
	v_mfma_f32_16x16x32_bf16 v[96:99], v[186:189], v[154:157], v[96:99]
	v_mfma_f32_16x16x32_bf16 v[124:127], v[166:169], v[150:153], v[124:127]
	v_mfma_f32_16x16x32_bf16 v[120:123], v[166:169], v[158:161], v[120:123]
	v_mfma_f32_16x16x32_bf16 v[116:119], v[174:177], v[150:153], v[116:119]
	v_mfma_f32_16x16x32_bf16 v[112:115], v[174:177], v[158:161], v[112:115]
	v_mfma_f32_16x16x32_bf16 v[108:111], v[182:185], v[150:153], v[108:111]
	v_mfma_f32_16x16x32_bf16 v[104:107], v[182:185], v[158:161], v[104:107]
	v_mfma_f32_16x16x32_bf16 v[100:103], v[196:199], v[150:153], v[100:103]
	v_mfma_f32_16x16x32_bf16 v[96:99], v[196:199], v[158:161], v[96:99]
	s_barrier
	s_add_u32 s53, s0, s38
	s_addc_u32 s54, s1, s39
	s_add_u32 s50, s53, 0x100
	v_add_u32_e32 v190, s33, v137
	s_addc_u32 s51, s54, 0
	ds_read_b128 v[200:203], v190
	ds_read_b128 v[204:207], v190 offset:1024
	ds_read_b128 v[208:211], v190 offset:2048
	ds_read_b128 v[212:215], v190 offset:3072
	v_lshl_add_u64 v[190:191], s[50:51], 0, v[192:193]
	v_readfirstlane_b32 s50, v129
	s_mov_b32 m0, s50
	v_readfirstlane_b32 s50, v130
	global_load_lds_dwordx4 v[190:191], off
	v_lshl_add_u64 v[190:191], v[190:191], 0, s[4:5]
	s_mov_b32 m0, s50
	s_nop 0
	global_load_lds_dwordx4 v[190:191], off
	s_barrier
	s_waitcnt lgkmcnt(0)
	s_waitcnt lgkmcnt(0)
	v_mfma_f32_16x16x32_bf16 v[92:95], v[162:165], v[200:203], v[92:95]
	v_mfma_f32_16x16x32_bf16 v[88:91], v[162:165], v[208:211], v[88:91]
	v_mfma_f32_16x16x32_bf16 v[84:87], v[170:173], v[200:203], v[84:87]
	v_mfma_f32_16x16x32_bf16 v[80:83], v[170:173], v[208:211], v[80:83]
	v_mfma_f32_16x16x32_bf16 v[76:79], v[178:181], v[200:203], v[76:79]
	v_mfma_f32_16x16x32_bf16 v[72:75], v[178:181], v[208:211], v[72:75]
	v_mfma_f32_16x16x32_bf16 v[68:71], v[186:189], v[200:203], v[68:71]
	v_mfma_f32_16x16x32_bf16 v[64:67], v[186:189], v[208:211], v[64:67]
	v_mfma_f32_16x16x32_bf16 v[92:95], v[166:169], v[204:207], v[92:95]
	v_mfma_f32_16x16x32_bf16 v[88:91], v[166:169], v[212:215], v[88:91]
	v_mfma_f32_16x16x32_bf16 v[84:87], v[174:177], v[204:207], v[84:87]
	v_mfma_f32_16x16x32_bf16 v[80:83], v[174:177], v[212:215], v[80:83]
	v_mfma_f32_16x16x32_bf16 v[76:79], v[182:185], v[204:207], v[76:79]
	v_mfma_f32_16x16x32_bf16 v[72:75], v[182:185], v[212:215], v[72:75]
	v_mfma_f32_16x16x32_bf16 v[68:71], v[196:199], v[204:207], v[68:71]
	v_mfma_f32_16x16x32_bf16 v[64:67], v[196:199], v[212:215], v[64:67]
	s_add_u32 s55, s2, s38
	s_addc_u32 s72, s3, s39
	s_add_u32 s50, s55, 0x100
	s_addc_u32 s51, s72, 0
	v_lshl_add_u64 v[190:191], s[50:51], 0, v[192:193]
	v_readfirstlane_b32 s50, v131
	s_mov_b32 m0, s50
	v_readfirstlane_b32 s50, v132
	s_barrier
	ds_read_b128 v[162:165], v128 offset:16384
	ds_read_b128 v[166:169], v128 offset:17408
	ds_read_b128 v[170:173], v128 offset:18432
	ds_read_b128 v[174:177], v128 offset:19456
	ds_read_b128 v[178:181], v128 offset:20480
	ds_read_b128 v[182:185], v128 offset:21504
	ds_read_b128 v[186:189], v128 offset:22528
	ds_read_b128 v[196:199], v128 offset:23552
	global_load_lds_dwordx4 v[190:191], off
	v_lshl_add_u64 v[190:191], v[190:191], 0, s[4:5]
	s_mov_b32 m0, s50
	s_nop 0
	global_load_lds_dwordx4 v[190:191], off
	s_barrier
	s_waitcnt lgkmcnt(0)
	s_waitcnt lgkmcnt(0)
	v_mfma_f32_16x16x32_bf16 v[60:63], v[162:165], v[146:149], v[60:63]
	v_mfma_f32_16x16x32_bf16 v[56:59], v[162:165], v[154:157], v[56:59]
	v_mfma_f32_16x16x32_bf16 v[52:55], v[170:173], v[146:149], v[52:55]
	v_mfma_f32_16x16x32_bf16 v[48:51], v[170:173], v[154:157], v[48:51]
	v_mfma_f32_16x16x32_bf16 v[44:47], v[178:181], v[146:149], v[44:47]
	v_mfma_f32_16x16x32_bf16 v[40:43], v[178:181], v[154:157], v[40:43]
	v_mfma_f32_16x16x32_bf16 v[36:39], v[186:189], v[146:149], v[36:39]
	v_mfma_f32_16x16x32_bf16 v[32:35], v[186:189], v[154:157], v[32:35]
	v_mfma_f32_16x16x32_bf16 v[60:63], v[166:169], v[150:153], v[60:63]
	v_mfma_f32_16x16x32_bf16 v[56:59], v[166:169], v[158:161], v[56:59]
	v_mfma_f32_16x16x32_bf16 v[52:55], v[174:177], v[150:153], v[52:55]
	v_mfma_f32_16x16x32_bf16 v[48:51], v[174:177], v[158:161], v[48:51]
	v_mfma_f32_16x16x32_bf16 v[44:47], v[182:185], v[150:153], v[44:47]
	v_mfma_f32_16x16x32_bf16 v[40:43], v[182:185], v[158:161], v[40:43]
	v_mfma_f32_16x16x32_bf16 v[36:39], v[196:199], v[150:153], v[36:39]
	v_mfma_f32_16x16x32_bf16 v[32:35], v[196:199], v[158:161], v[32:35]
	s_barrier
	s_add_u32 s73, s12, s38
	s_addc_u32 s74, s13, s39
	s_add_u32 s50, s73, 0x100
	s_addc_u32 s51, s74, 0
	v_lshl_add_u64 v[146:147], s[50:51], 0, v[192:193]
	v_readfirstlane_b32 s50, v133
	s_mov_b32 m0, s50
	v_readfirstlane_b32 s50, v134
	global_load_lds_dwordx4 v[146:147], off
	v_lshl_add_u64 v[146:147], v[146:147], 0, s[4:5]
	s_mov_b32 m0, s50
	s_nop 0
	global_load_lds_dwordx4 v[146:147], off
	s_waitcnt vmcnt(6)
	s_barrier
	v_mfma_f32_16x16x32_bf16 v[28:31], v[162:165], v[200:203], v[28:31]
	v_mfma_f32_16x16x32_bf16 v[24:27], v[162:165], v[208:211], v[24:27]
	v_mfma_f32_16x16x32_bf16 v[20:23], v[170:173], v[200:203], v[20:23]
	v_mfma_f32_16x16x32_bf16 v[16:19], v[170:173], v[208:211], v[16:19]
	v_mfma_f32_16x16x32_bf16 v[12:15], v[178:181], v[200:203], v[12:15]
	v_mfma_f32_16x16x32_bf16 v[8:11], v[178:181], v[208:211], v[8:11]
	v_mfma_f32_16x16x32_bf16 v[4:7], v[186:189], v[200:203], v[4:7]
	v_mfma_f32_16x16x32_bf16 v[0:3], v[186:189], v[208:211], v[0:3]
	v_mfma_f32_16x16x32_bf16 v[28:31], v[166:169], v[204:207], v[28:31]
	v_mfma_f32_16x16x32_bf16 v[24:27], v[166:169], v[212:215], v[24:27]
	v_mfma_f32_16x16x32_bf16 v[20:23], v[174:177], v[204:207], v[20:23]
	v_mfma_f32_16x16x32_bf16 v[16:19], v[174:177], v[212:215], v[16:19]
	v_mfma_f32_16x16x32_bf16 v[12:15], v[182:185], v[204:207], v[12:15]
	v_mfma_f32_16x16x32_bf16 v[8:11], v[182:185], v[212:215], v[8:11]
	v_mfma_f32_16x16x32_bf16 v[4:7], v[196:199], v[204:207], v[4:7]
	v_mfma_f32_16x16x32_bf16 v[0:3], v[196:199], v[212:215], v[0:3]
	v_add_u32_e32 v158, s93, v137
	s_barrier
	ds_read_b128 v[146:149], v158
	ds_read_b128 v[150:153], v158 offset:1024
	ds_read_b128 v[154:157], v158 offset:2048
	ds_read_b128 v[158:161], v158 offset:3072
	s_add_u32 s50, s49, 0x100
	s_addc_u32 s51, s52, 0
	v_readfirstlane_b32 s49, v135
	v_lshl_add_u64 v[190:191], s[50:51], 0, v[192:193]
	s_mov_b32 m0, s49
	v_readfirstlane_b32 s49, v136
	ds_read_b128 v[162:165], v128 offset:32768
	ds_read_b128 v[166:169], v128 offset:33792
	ds_read_b128 v[170:173], v128 offset:34816
	ds_read_b128 v[174:177], v128 offset:35840
	ds_read_b128 v[178:181], v128 offset:36864
	ds_read_b128 v[182:185], v128 offset:37888
	ds_read_b128 v[186:189], v128 offset:38912
	ds_read_b128 v[196:199], v128 offset:39936
	global_load_lds_dwordx4 v[190:191], off
	v_lshl_add_u64 v[190:191], v[190:191], 0, s[4:5]
	s_mov_b32 m0, s49
	s_nop 0
	global_load_lds_dwordx4 v[190:191], off
	s_waitcnt lgkmcnt(8)
	s_barrier
	s_waitcnt lgkmcnt(0)
	s_waitcnt lgkmcnt(0)
	v_mfma_f32_16x16x32_bf16 v[124:127], v[162:165], v[146:149], v[124:127]
	v_mfma_f32_16x16x32_bf16 v[120:123], v[162:165], v[154:157], v[120:123]
	v_mfma_f32_16x16x32_bf16 v[116:119], v[170:173], v[146:149], v[116:119]
	v_mfma_f32_16x16x32_bf16 v[112:115], v[170:173], v[154:157], v[112:115]
	v_mfma_f32_16x16x32_bf16 v[108:111], v[178:181], v[146:149], v[108:111]
	v_mfma_f32_16x16x32_bf16 v[104:107], v[178:181], v[154:157], v[104:107]
	v_mfma_f32_16x16x32_bf16 v[100:103], v[186:189], v[146:149], v[100:103]
	v_mfma_f32_16x16x32_bf16 v[96:99], v[186:189], v[154:157], v[96:99]
	v_mfma_f32_16x16x32_bf16 v[124:127], v[166:169], v[150:153], v[124:127]
	v_mfma_f32_16x16x32_bf16 v[120:123], v[166:169], v[158:161], v[120:123]
	v_mfma_f32_16x16x32_bf16 v[116:119], v[174:177], v[150:153], v[116:119]
	v_mfma_f32_16x16x32_bf16 v[112:115], v[174:177], v[158:161], v[112:115]
	v_mfma_f32_16x16x32_bf16 v[108:111], v[182:185], v[150:153], v[108:111]
	v_mfma_f32_16x16x32_bf16 v[104:107], v[182:185], v[158:161], v[104:107]
	v_mfma_f32_16x16x32_bf16 v[100:103], v[196:199], v[150:153], v[100:103]
	v_mfma_f32_16x16x32_bf16 v[96:99], v[196:199], v[158:161], v[96:99]
	s_barrier
	s_add_u32 s50, s53, 0x180
	v_add_u32_e32 v190, s89, v137
	s_addc_u32 s51, s54, 0
	v_readfirstlane_b32 s49, v138
	ds_read_b128 v[200:203], v190
	ds_read_b128 v[204:207], v190 offset:1024
	ds_read_b128 v[208:211], v190 offset:2048
	ds_read_b128 v[212:215], v190 offset:3072
	v_lshl_add_u64 v[190:191], s[50:51], 0, v[192:193]
	s_mov_b32 m0, s49
	v_readfirstlane_b32 s49, v139
	global_load_lds_dwordx4 v[190:191], off
	v_lshl_add_u64 v[190:191], v[190:191], 0, s[4:5]
	s_mov_b32 m0, s49
	s_nop 0
	global_load_lds_dwordx4 v[190:191], off
	s_barrier
	s_waitcnt lgkmcnt(0)
	s_waitcnt lgkmcnt(0)
	v_mfma_f32_16x16x32_bf16 v[92:95], v[162:165], v[200:203], v[92:95]
	v_mfma_f32_16x16x32_bf16 v[88:91], v[162:165], v[208:211], v[88:91]
	v_mfma_f32_16x16x32_bf16 v[84:87], v[170:173], v[200:203], v[84:87]
	v_mfma_f32_16x16x32_bf16 v[80:83], v[170:173], v[208:211], v[80:83]
	v_mfma_f32_16x16x32_bf16 v[76:79], v[178:181], v[200:203], v[76:79]
	v_mfma_f32_16x16x32_bf16 v[72:75], v[178:181], v[208:211], v[72:75]
	v_mfma_f32_16x16x32_bf16 v[68:71], v[186:189], v[200:203], v[68:71]
	v_mfma_f32_16x16x32_bf16 v[64:67], v[186:189], v[208:211], v[64:67]
	v_mfma_f32_16x16x32_bf16 v[92:95], v[166:169], v[204:207], v[92:95]
	v_mfma_f32_16x16x32_bf16 v[88:91], v[166:169], v[212:215], v[88:91]
	v_mfma_f32_16x16x32_bf16 v[84:87], v[174:177], v[204:207], v[84:87]
	v_mfma_f32_16x16x32_bf16 v[80:83], v[174:177], v[212:215], v[80:83]
	v_mfma_f32_16x16x32_bf16 v[76:79], v[182:185], v[204:207], v[76:79]
	v_mfma_f32_16x16x32_bf16 v[72:75], v[182:185], v[212:215], v[72:75]
	v_mfma_f32_16x16x32_bf16 v[68:71], v[196:199], v[204:207], v[68:71]
	v_mfma_f32_16x16x32_bf16 v[64:67], v[196:199], v[212:215], v[64:67]
	s_add_u32 s50, s55, 0x180
	s_addc_u32 s51, s72, 0
	v_readfirstlane_b32 s49, v140
	v_lshl_add_u64 v[190:191], s[50:51], 0, v[192:193]
	s_mov_b32 m0, s49
	v_readfirstlane_b32 s49, v141
	s_barrier
	ds_read_b128 v[162:165], v128 offset:49152
	ds_read_b128 v[166:169], v128 offset:50176
	ds_read_b128 v[170:173], v128 offset:51200
	ds_read_b128 v[174:177], v128 offset:52224
	ds_read_b128 v[178:181], v128 offset:53248
	ds_read_b128 v[182:185], v128 offset:54272
	ds_read_b128 v[186:189], v128 offset:55296
	ds_read_b128 v[196:199], v128 offset:56320
	global_load_lds_dwordx4 v[190:191], off
	v_lshl_add_u64 v[190:191], v[190:191], 0, s[4:5]
	s_mov_b32 m0, s49
	s_nop 0
	global_load_lds_dwordx4 v[190:191], off
	s_barrier
	s_waitcnt lgkmcnt(0)
	s_waitcnt lgkmcnt(0)
	v_mfma_f32_16x16x32_bf16 v[60:63], v[162:165], v[146:149], v[60:63]
	v_mfma_f32_16x16x32_bf16 v[56:59], v[162:165], v[154:157], v[56:59]
	v_mfma_f32_16x16x32_bf16 v[52:55], v[170:173], v[146:149], v[52:55]
	v_mfma_f32_16x16x32_bf16 v[48:51], v[170:173], v[154:157], v[48:51]
	v_mfma_f32_16x16x32_bf16 v[44:47], v[178:181], v[146:149], v[44:47]
	v_mfma_f32_16x16x32_bf16 v[40:43], v[178:181], v[154:157], v[40:43]
	v_mfma_f32_16x16x32_bf16 v[36:39], v[186:189], v[146:149], v[36:39]
	v_mfma_f32_16x16x32_bf16 v[32:35], v[186:189], v[154:157], v[32:35]
	v_mfma_f32_16x16x32_bf16 v[60:63], v[166:169], v[150:153], v[60:63]
	v_mfma_f32_16x16x32_bf16 v[56:59], v[166:169], v[158:161], v[56:59]
	v_mfma_f32_16x16x32_bf16 v[52:55], v[174:177], v[150:153], v[52:55]
	v_mfma_f32_16x16x32_bf16 v[48:51], v[174:177], v[158:161], v[48:51]
	v_mfma_f32_16x16x32_bf16 v[44:47], v[182:185], v[150:153], v[44:47]
	v_mfma_f32_16x16x32_bf16 v[40:43], v[182:185], v[158:161], v[40:43]
	v_mfma_f32_16x16x32_bf16 v[36:39], v[196:199], v[150:153], v[36:39]
	v_mfma_f32_16x16x32_bf16 v[32:35], v[196:199], v[158:161], v[32:35]
	s_barrier
	s_add_u32 s50, s73, 0x180
	s_addc_u32 s51, s74, 0
	v_readfirstlane_b32 s49, v142
	v_lshl_add_u64 v[146:147], s[50:51], 0, v[192:193]
	s_mov_b32 m0, s49
	v_readfirstlane_b32 s49, v143
	global_load_lds_dwordx4 v[146:147], off
	v_lshl_add_u64 v[146:147], v[146:147], 0, s[4:5]
	s_mov_b32 m0, s49
	s_nop 0
	global_load_lds_dwordx4 v[146:147], off
	s_waitcnt vmcnt(6)
	s_barrier
	v_mfma_f32_16x16x32_bf16 v[28:31], v[162:165], v[200:203], v[28:31]
	v_mfma_f32_16x16x32_bf16 v[24:27], v[162:165], v[208:211], v[24:27]
	v_mfma_f32_16x16x32_bf16 v[20:23], v[170:173], v[200:203], v[20:23]
	v_mfma_f32_16x16x32_bf16 v[16:19], v[170:173], v[208:211], v[16:19]
	v_mfma_f32_16x16x32_bf16 v[12:15], v[178:181], v[200:203], v[12:15]
	v_mfma_f32_16x16x32_bf16 v[8:11], v[178:181], v[208:211], v[8:11]
	v_mfma_f32_16x16x32_bf16 v[4:7], v[186:189], v[200:203], v[4:7]
	v_mfma_f32_16x16x32_bf16 v[0:3], v[186:189], v[208:211], v[0:3]
	v_mfma_f32_16x16x32_bf16 v[28:31], v[166:169], v[204:207], v[28:31]
	v_mfma_f32_16x16x32_bf16 v[24:27], v[166:169], v[212:215], v[24:27]
	v_mfma_f32_16x16x32_bf16 v[20:23], v[174:177], v[204:207], v[20:23]
	v_mfma_f32_16x16x32_bf16 v[16:19], v[174:177], v[212:215], v[16:19]
	v_mfma_f32_16x16x32_bf16 v[12:15], v[182:185], v[204:207], v[12:15]
	v_mfma_f32_16x16x32_bf16 v[8:11], v[182:185], v[212:215], v[8:11]
	v_mfma_f32_16x16x32_bf16 v[4:7], v[196:199], v[204:207], v[4:7]
	v_mfma_f32_16x16x32_bf16 v[0:3], v[196:199], v[212:215], v[0:3]
	s_add_i32 s48, s48, 2
	s_add_u32 s38, s38, 0x100
	s_addc_u32 s39, s39, 0
	s_cmp_lt_u32 s48, 12
	s_barrier
	s_cbranch_scc1 .LBB0_362
	v_add_u32_e32 v129, 0, v137
	s_add_u32 s0, s36, 0x780
	v_add_u32_e32 v142, 0x10000, v129
	s_addc_u32 s1, s37, 0
	ds_read_b128 v[130:133], v142
	ds_read_b128 v[134:137], v142 offset:1024
	ds_read_b128 v[138:141], v142 offset:2048
	ds_read_b128 v[146:149], v142 offset:3072
	ds_read_b128 v[150:153], v128
	ds_read_b128 v[154:157], v128 offset:1024
	ds_read_b128 v[158:161], v128 offset:2048
	ds_read_b128 v[162:165], v128 offset:3072
	ds_read_b128 v[166:169], v128 offset:4096
	ds_read_b128 v[170:173], v128 offset:5120
	ds_read_b128 v[174:177], v128 offset:6144
	ds_read_b128 v[178:181], v128 offset:7168
	v_lshl_add_u64 v[142:143], s[0:1], 0, v[192:193]
	v_readfirstlane_b32 s0, v144
	s_mov_b32 m0, s0
	v_readfirstlane_b32 s0, v145
	global_load_lds_dwordx4 v[142:143], off
	v_lshl_add_u64 v[142:143], v[142:143], 0, s[4:5]
	s_mov_b32 m0, s0
	s_nop 0
	global_load_lds_dwordx4 v[142:143], off
	s_barrier
	s_waitcnt lgkmcnt(0)
	s_setprio 1
	s_waitcnt lgkmcnt(0)
	v_mfma_f32_16x16x32_bf16 v[124:127], v[150:153], v[130:133], v[124:127]
	v_mfma_f32_16x16x32_bf16 v[120:123], v[150:153], v[138:141], v[120:123]
	v_mfma_f32_16x16x32_bf16 v[116:119], v[158:161], v[130:133], v[116:119]
	v_mfma_f32_16x16x32_bf16 v[112:115], v[158:161], v[138:141], v[112:115]
	v_mfma_f32_16x16x32_bf16 v[108:111], v[166:169], v[130:133], v[108:111]
	v_mfma_f32_16x16x32_bf16 v[104:107], v[166:169], v[138:141], v[104:107]
	v_mfma_f32_16x16x32_bf16 v[100:103], v[174:177], v[130:133], v[100:103]
	v_mfma_f32_16x16x32_bf16 v[96:99], v[174:177], v[138:141], v[96:99]
	v_mfma_f32_16x16x32_bf16 v[124:127], v[154:157], v[134:137], v[124:127]
	v_mfma_f32_16x16x32_bf16 v[120:123], v[154:157], v[146:149], v[120:123]
	v_mfma_f32_16x16x32_bf16 v[116:119], v[162:165], v[134:137], v[116:119]
	v_mfma_f32_16x16x32_bf16 v[112:115], v[162:165], v[146:149], v[112:115]
	v_mfma_f32_16x16x32_bf16 v[108:111], v[170:173], v[134:137], v[108:111]
	v_mfma_f32_16x16x32_bf16 v[104:107], v[170:173], v[146:149], v[104:107]
	v_mfma_f32_16x16x32_bf16 v[100:103], v[178:181], v[134:137], v[100:103]
	v_mfma_f32_16x16x32_bf16 v[96:99], v[178:181], v[146:149], v[96:99]
	s_setprio 0
	v_add_u32_e32 v190, 0x14000, v129
	s_barrier
	ds_read_b128 v[142:145], v190
	ds_read_b128 v[182:185], v190 offset:1024
	ds_read_b128 v[186:189], v190 offset:2048
	ds_read_b128 v[196:199], v190 offset:3072
	s_barrier
	s_waitcnt lgkmcnt(0)
	s_setprio 1
	s_waitcnt lgkmcnt(0)
	v_mfma_f32_16x16x32_bf16 v[92:95], v[150:153], v[142:145], v[92:95]
	v_mfma_f32_16x16x32_bf16 v[88:91], v[150:153], v[186:189], v[88:91]
	v_mfma_f32_16x16x32_bf16 v[84:87], v[158:161], v[142:145], v[84:87]
	v_mfma_f32_16x16x32_bf16 v[80:83], v[158:161], v[186:189], v[80:83]
	v_mfma_f32_16x16x32_bf16 v[76:79], v[166:169], v[142:145], v[76:79]
	v_mfma_f32_16x16x32_bf16 v[72:75], v[166:169], v[186:189], v[72:75]
	v_mfma_f32_16x16x32_bf16 v[68:71], v[174:177], v[142:145], v[68:71]
	v_mfma_f32_16x16x32_bf16 v[64:67], v[174:177], v[186:189], v[64:67]
	v_mfma_f32_16x16x32_bf16 v[200:203], v[154:157], v[182:185], v[92:95]
	v_mfma_f32_16x16x32_bf16 v[150:153], v[154:157], v[196:199], v[88:91]
	v_mfma_f32_16x16x32_bf16 v[154:157], v[162:165], v[182:185], v[84:87]
	v_mfma_f32_16x16x32_bf16 v[158:161], v[162:165], v[196:199], v[80:83]
	v_mfma_f32_16x16x32_bf16 v[162:165], v[170:173], v[182:185], v[76:79]
	v_mfma_f32_16x16x32_bf16 v[166:169], v[170:173], v[196:199], v[72:75]
	v_mfma_f32_16x16x32_bf16 v[170:173], v[178:181], v[182:185], v[68:71]
	v_mfma_f32_16x16x32_bf16 v[174:177], v[178:181], v[196:199], v[64:67]
	s_setprio 0
	s_barrier
	s_nop 0
	ds_read_b128 v[64:67], v128 offset:16384
	ds_read_b128 v[68:71], v128 offset:17408
	ds_read_b128 v[72:75], v128 offset:18432
	ds_read_b128 v[76:79], v128 offset:19456
	ds_read_b128 v[80:83], v128 offset:20480
	ds_read_b128 v[84:87], v128 offset:21504
	ds_read_b128 v[88:91], v128 offset:22528
	ds_read_b128 v[92:95], v128 offset:23552
	s_waitcnt vmcnt(4)
	s_barrier
	s_waitcnt lgkmcnt(0)
	s_setprio 1
	s_waitcnt lgkmcnt(0)
	v_mfma_f32_16x16x32_bf16 v[60:63], v[64:67], v[130:133], v[60:63]
	v_mfma_f32_16x16x32_bf16 v[56:59], v[64:67], v[138:141], v[56:59]
	v_mfma_f32_16x16x32_bf16 v[52:55], v[72:75], v[130:133], v[52:55]
	v_mfma_f32_16x16x32_bf16 v[48:51], v[72:75], v[138:141], v[48:51]
	v_mfma_f32_16x16x32_bf16 v[44:47], v[80:83], v[130:133], v[44:47]
	v_mfma_f32_16x16x32_bf16 v[40:43], v[80:83], v[138:141], v[40:43]
	v_mfma_f32_16x16x32_bf16 v[36:39], v[88:91], v[130:133], v[36:39]
	v_mfma_f32_16x16x32_bf16 v[32:35], v[88:91], v[138:141], v[32:35]
	v_mfma_f32_16x16x32_bf16 v[60:63], v[68:71], v[134:137], v[60:63]
	v_mfma_f32_16x16x32_bf16 v[56:59], v[68:71], v[146:149], v[56:59]
	v_mfma_f32_16x16x32_bf16 v[52:55], v[76:79], v[134:137], v[52:55]
	v_mfma_f32_16x16x32_bf16 v[48:51], v[76:79], v[146:149], v[48:51]
	v_mfma_f32_16x16x32_bf16 v[44:47], v[84:87], v[134:137], v[44:47]
	v_mfma_f32_16x16x32_bf16 v[40:43], v[84:87], v[146:149], v[40:43]
	v_mfma_f32_16x16x32_bf16 v[36:39], v[92:95], v[134:137], v[36:39]
	v_mfma_f32_16x16x32_bf16 v[32:35], v[92:95], v[146:149], v[32:35]
	s_setprio 0
	s_setprio 1
	v_mfma_f32_16x16x32_bf16 v[28:31], v[64:67], v[142:145], v[28:31]
	v_mfma_f32_16x16x32_bf16 v[24:27], v[64:67], v[186:189], v[24:27]
	v_mfma_f32_16x16x32_bf16 v[20:23], v[72:75], v[142:145], v[20:23]
	v_mfma_f32_16x16x32_bf16 v[16:19], v[72:75], v[186:189], v[16:19]
	v_mfma_f32_16x16x32_bf16 v[12:15], v[80:83], v[142:145], v[12:15]
	v_mfma_f32_16x16x32_bf16 v[8:11], v[80:83], v[186:189], v[8:11]
	v_mfma_f32_16x16x32_bf16 v[4:7], v[88:91], v[142:145], v[4:7]
	v_mfma_f32_16x16x32_bf16 v[0:3], v[88:91], v[186:189], v[0:3]
	v_mfma_f32_16x16x32_bf16 v[130:133], v[68:71], v[182:185], v[28:31]
	v_mfma_f32_16x16x32_bf16 v[134:137], v[68:71], v[196:199], v[24:27]
	v_mfma_f32_16x16x32_bf16 v[138:141], v[76:79], v[182:185], v[20:23]
	v_mfma_f32_16x16x32_bf16 v[146:149], v[76:79], v[196:199], v[16:19]
	v_mfma_f32_16x16x32_bf16 v[178:181], v[84:87], v[182:185], v[12:15]
	v_mfma_f32_16x16x32_bf16 v[204:207], v[84:87], v[196:199], v[8:11]
	v_mfma_f32_16x16x32_bf16 v[142:145], v[92:95], v[182:185], v[4:7]
	v_mfma_f32_16x16x32_bf16 v[182:185], v[92:95], v[196:199], v[0:3]
	s_setprio 0
	s_nop 1
	v_add_u32_e32 v0, 0x18000, v129
	s_barrier
	ds_read_b128 v[24:27], v0
	ds_read_b128 v[28:31], v0 offset:1024
	ds_read_b128 v[186:189], v0 offset:2048
	ds_read_b128 v[196:199], v0 offset:3072
	ds_read_b128 v[0:3], v128 offset:32768
	ds_read_b128 v[4:7], v128 offset:33792
	ds_read_b128 v[8:11], v128 offset:34816
	ds_read_b128 v[12:15], v128 offset:35840
	ds_read_b128 v[16:19], v128 offset:36864
	ds_read_b128 v[20:23], v128 offset:37888
	ds_read_b128 v[208:211], v128 offset:38912
	ds_read_b128 v[212:215], v128 offset:39936
	s_waitcnt vmcnt(2)
	s_barrier
	s_waitcnt lgkmcnt(0)
	s_setprio 1
	s_waitcnt lgkmcnt(0)
	v_mfma_f32_16x16x32_bf16 v[64:67], v[0:3], v[24:27], v[124:127]
	v_mfma_f32_16x16x32_bf16 v[92:95], v[4:7], v[28:31], v[64:67]
	v_mfma_f32_16x16x32_bf16 v[64:67], v[0:3], v[186:189], v[120:123]
	v_mfma_f32_16x16x32_bf16 v[68:71], v[8:11], v[24:27], v[116:119]
	v_mfma_f32_16x16x32_bf16 v[72:75], v[8:11], v[186:189], v[112:115]
	v_mfma_f32_16x16x32_bf16 v[76:79], v[16:19], v[24:27], v[108:111]
	v_mfma_f32_16x16x32_bf16 v[80:83], v[16:19], v[186:189], v[104:107]
	v_mfma_f32_16x16x32_bf16 v[84:87], v[208:211], v[24:27], v[100:103]
	v_mfma_f32_16x16x32_bf16 v[88:91], v[208:211], v[186:189], v[96:99]
	v_mfma_f32_16x16x32_bf16 v[64:67], v[4:7], v[196:199], v[64:67]
	v_mfma_f32_16x16x32_bf16 v[68:71], v[12:15], v[28:31], v[68:71]
	v_mfma_f32_16x16x32_bf16 v[72:75], v[12:15], v[196:199], v[72:75]
	v_mfma_f32_16x16x32_bf16 v[76:79], v[20:23], v[28:31], v[76:79]
	v_mfma_f32_16x16x32_bf16 v[80:83], v[20:23], v[196:199], v[80:83]
	v_mfma_f32_16x16x32_bf16 v[84:87], v[212:215], v[28:31], v[84:87]
	v_mfma_f32_16x16x32_bf16 v[88:91], v[212:215], v[196:199], v[88:91]
	s_setprio 0
	v_add_u32_e32 v96, 0x1c000, v129
	s_barrier
	ds_read_b128 v[216:219], v96
	ds_read_b128 v[220:223], v96 offset:1024
	ds_read_b128 v[224:227], v96 offset:2048
	ds_read_b128 v[228:231], v96 offset:3072
	s_waitcnt vmcnt(0)
	s_barrier
	s_waitcnt lgkmcnt(0)
	s_setprio 1
	s_waitcnt lgkmcnt(0)
	v_mfma_f32_16x16x32_bf16 v[96:99], v[0:3], v[216:219], v[200:203]
	v_mfma_f32_16x16x32_bf16 v[0:3], v[0:3], v[224:227], v[150:153]
	v_mfma_f32_16x16x32_bf16 v[124:127], v[4:7], v[220:223], v[96:99]
	v_mfma_f32_16x16x32_bf16 v[96:99], v[4:7], v[228:231], v[0:3]
	v_mfma_f32_16x16x32_bf16 v[0:3], v[8:11], v[216:219], v[154:157]
	v_mfma_f32_16x16x32_bf16 v[100:103], v[12:15], v[220:223], v[0:3]
	v_mfma_f32_16x16x32_bf16 v[0:3], v[8:11], v[224:227], v[158:161]
	v_mfma_f32_16x16x32_bf16 v[104:107], v[12:15], v[228:231], v[0:3]
	v_mfma_f32_16x16x32_bf16 v[0:3], v[16:19], v[216:219], v[162:165]
	v_mfma_f32_16x16x32_bf16 v[108:111], v[20:23], v[220:223], v[0:3]
	v_mfma_f32_16x16x32_bf16 v[0:3], v[16:19], v[224:227], v[166:169]
	v_mfma_f32_16x16x32_bf16 v[112:115], v[20:23], v[228:231], v[0:3]
	v_mfma_f32_16x16x32_bf16 v[0:3], v[208:211], v[216:219], v[170:173]
	v_mfma_f32_16x16x32_bf16 v[116:119], v[212:215], v[220:223], v[0:3]
	v_mfma_f32_16x16x32_bf16 v[0:3], v[208:211], v[224:227], v[174:177]
	v_mfma_f32_16x16x32_bf16 v[120:123], v[212:215], v[228:231], v[0:3]
	s_setprio 0
	s_barrier
	ds_read_b128 v[150:153], v128 offset:49152
	ds_read_b128 v[154:157], v128 offset:50176
	ds_read_b128 v[158:161], v128 offset:51200
	ds_read_b128 v[162:165], v128 offset:52224
	ds_read_b128 v[166:169], v128 offset:53248
	ds_read_b128 v[170:173], v128 offset:54272
	ds_read_b128 v[174:177], v128 offset:55296
	ds_read_b128 v[200:203], v128 offset:56320
	s_barrier
	s_waitcnt lgkmcnt(0)
	s_setprio 1
	s_waitcnt lgkmcnt(0)
	v_mfma_f32_16x16x32_bf16 v[0:3], v[150:153], v[24:27], v[60:63]
	v_mfma_f32_16x16x32_bf16 v[8:11], v[158:161], v[24:27], v[52:55]
	v_mfma_f32_16x16x32_bf16 v[16:19], v[166:169], v[24:27], v[44:47]
	v_mfma_f32_16x16x32_bf16 v[24:27], v[174:177], v[24:27], v[36:39]
	v_mfma_f32_16x16x32_bf16 v[0:3], v[154:157], v[28:31], v[0:3]
	v_mfma_f32_16x16x32_bf16 v[4:7], v[150:153], v[186:189], v[56:59]
	v_mfma_f32_16x16x32_bf16 v[8:11], v[162:165], v[28:31], v[8:11]
	v_mfma_f32_16x16x32_bf16 v[12:15], v[158:161], v[186:189], v[48:51]
	v_mfma_f32_16x16x32_bf16 v[16:19], v[170:173], v[28:31], v[16:19]
	v_mfma_f32_16x16x32_bf16 v[20:23], v[166:169], v[186:189], v[40:43]
	v_mfma_f32_16x16x32_bf16 v[24:27], v[200:203], v[28:31], v[24:27]
	v_mfma_f32_16x16x32_bf16 v[28:31], v[174:177], v[186:189], v[32:35]
	v_mfma_f32_16x16x32_bf16 v[4:7], v[154:157], v[196:199], v[4:7]
	v_mfma_f32_16x16x32_bf16 v[12:15], v[162:165], v[196:199], v[12:15]
	v_mfma_f32_16x16x32_bf16 v[20:23], v[170:173], v[196:199], v[20:23]
	v_mfma_f32_16x16x32_bf16 v[28:31], v[200:203], v[196:199], v[28:31]
	s_setprio 0
	s_setprio 1
	v_mfma_f32_16x16x32_bf16 v[32:35], v[150:153], v[216:219], v[130:133]
	v_mfma_f32_16x16x32_bf16 v[36:39], v[150:153], v[224:227], v[134:137]
	v_mfma_f32_16x16x32_bf16 v[40:43], v[158:161], v[216:219], v[138:141]
	v_mfma_f32_16x16x32_bf16 v[44:47], v[158:161], v[224:227], v[146:149]
	v_mfma_f32_16x16x32_bf16 v[48:51], v[166:169], v[216:219], v[178:181]
	v_mfma_f32_16x16x32_bf16 v[52:55], v[166:169], v[224:227], v[204:207]
	v_mfma_f32_16x16x32_bf16 v[56:59], v[174:177], v[216:219], v[142:145]
	v_mfma_f32_16x16x32_bf16 v[60:63], v[174:177], v[224:227], v[182:185]
	v_mfma_f32_16x16x32_bf16 v[32:35], v[154:157], v[220:223], v[32:35]
	v_mfma_f32_16x16x32_bf16 v[36:39], v[154:157], v[228:231], v[36:39]
	v_mfma_f32_16x16x32_bf16 v[40:43], v[162:165], v[220:223], v[40:43]
	v_mfma_f32_16x16x32_bf16 v[44:47], v[162:165], v[228:231], v[44:47]
	v_mfma_f32_16x16x32_bf16 v[48:51], v[170:173], v[220:223], v[48:51]
	v_mfma_f32_16x16x32_bf16 v[52:55], v[170:173], v[228:231], v[52:55]
	v_mfma_f32_16x16x32_bf16 v[56:59], v[200:203], v[220:223], v[56:59]
	v_mfma_f32_16x16x32_bf16 v[60:63], v[200:203], v[228:231], v[60:63]
	s_setprio 0
	s_cmpk_gt_u32 s47, 0xff
	s_barrier
	s_cbranch_scc1 .LBB0_365
	s_barrier

.Lgsel_done:
	v_cndmask_b32_e64 v16, v16, 0, s[44:45]
	v_cndmask_b32_e64 v17, v17, 0, s[46:47]
	v_cndmask_b32_e64 v18, v18, 0, s[48:49]
	v_cndmask_b32_e64 v19, v19, 0, s[50:51]
	ds_write_b16 v152, v16 offset:24576
	ds_write_b16 v152, v17 offset:24656
	ds_write_b16 v152, v18 offset:24736
	ds_write_b16 v152, v19 offset:24816
	s_waitcnt lgkmcnt(0)
	s_barrier
	ds_read_b128 v[0:3], v154 offset:9216
	ds_read_b128 v[56:59], v151 offset:96
	ds_read_b128 v[4:7], v154 offset:24576
	ds_read_b128 v[28:31], v154 offset:9248
	s_waitcnt lgkmcnt(3)
	v_mfma_f32_32x32x16_bf16 v[8:23], v[0:3], v[228:231], 0
	ds_read_b128 v[162:165], v154 offset:24608
	ds_read_b128 v[166:169], v182 offset:27136
	ds_read_b128 v[64:67], v151 offset:32
	ds_read_b128 v[60:63], v151 offset:64
	ds_read_b128 v[170:173], v151
	ds_read_b128 v[0:3], v126 offset:45568
	ds_read_b128 v[158:161], v126 offset:45600
	ds_read_b128 v[184:187], v126 offset:45728
	ds_read_b128 v[196:199], v126 offset:45792
	s_waitcnt lgkmcnt(9)
	v_mfma_f32_32x32x16_bf16 v[8:23], v[28:31], v[240:243], v[8:23]
	s_waitcnt lgkmcnt(0)
	s_nop 10
	v_pk_fma_f32 v[74:75], v[74:75], v[0:1], v[8:9]
	v_pk_fma_f32 v[76:77], v[76:77], v[2:3], v[10:11]
	v_cvt_pk_bf16_f32 v0, v74, v75
	v_cvt_pk_bf16_f32 v1, v76, v77
	ds_write_b64 v109, v[0:1] offset:27136
	s_waitcnt lgkmcnt(0)
	v_pk_fma_f32 v[78:79], v[78:79], v[158:159], v[12:13]
	v_pk_fma_f32 v[80:81], v[80:81], v[160:161], v[14:15]
	v_cvt_pk_bf16_f32 v0, v78, v79
	v_cvt_pk_bf16_f32 v1, v80, v81
	ds_write_b64 v155, v[0:1] offset:27136
	ds_read_b128 v[28:31], v126 offset:45632
	ds_read_b128 v[68:71], v182 offset:27168
	v_mfma_f32_32x32x16_bf16 v[0:15], v[4:7], v[228:231], 0
	s_waitcnt lgkmcnt(1)
	v_fma_f32 v82, v82, v28, v16
	v_fma_f32 v83, v83, v29, v17
	v_fma_f32 v84, v84, v30, v18
	v_fma_f32 v85, v85, v31, v19
	v_cvt_pk_bf16_f32 v16, v82, v83
	v_cvt_pk_bf16_f32 v17, v84, v85
	ds_write_b64 v156, v[16:17] offset:27136
	ds_read_b128 v[16:19], v126 offset:45664
	v_mfma_f32_32x32x16_bf16 v[0:15], v[162:165], v[240:243], v[0:15]
	s_waitcnt lgkmcnt(0)
	v_fma_f32 v86, v86, v16, v20
	v_fma_f32 v87, v87, v17, v21
	v_fma_f32 v88, v88, v18, v22
	v_fma_f32 v89, v89, v19, v23
	v_cvt_pk_bf16_f32 v16, v86, v87
	v_cvt_pk_bf16_f32 v17, v88, v89
	ds_write_b64 v157, v[16:17] offset:27136
	ds_read_b128 v[16:19], v154 offset:11776
	ds_read_b128 v[162:165], v126 offset:45696
	s_waitcnt lgkmcnt(1)
	v_mfma_f32_32x32x16_bf16 v[16:31], v[16:19], v[228:231], 0
	ds_read_b128 v[174:177], v154 offset:11808
	ds_read_b128 v[178:181], v182 offset:27200
	s_waitcnt lgkmcnt(1)
	v_mfma_f32_32x32x16_bf16 v[16:31], v[174:177], v[240:243], v[16:31]
	v_mfma_f32_32x32x16_bf16 v[0:15], v[170:173], v[166:169], v[0:15]
	s_nop 10
	v_fma_f32 v90, v90, v162, v16
	v_fma_f32 v91, v91, v163, v17
	v_fma_f32 v92, v92, v164, v18
	v_fma_f32 v93, v93, v165, v19
	v_cvt_pk_bf16_f32 v16, v90, v91
	v_cvt_pk_bf16_f32 v17, v92, v93
	ds_write_b64 v109, v[16:17] offset:27200
	s_waitcnt lgkmcnt(0)
	v_pk_fma_f32 v[94:95], v[94:95], v[184:185], v[20:21]
	v_mfma_f32_32x32x16_bf16 v[0:15], v[64:67], v[68:71], v[0:15]
	v_fma_f32 v96, v96, v186, v22
	v_fma_f32 v97, v97, v187, v23
	v_cvt_pk_bf16_f32 v16, v94, v95
	v_cvt_pk_bf16_f32 v17, v96, v97
	ds_write_b64 v109, v[16:17] offset:27216
	ds_read_b128 v[16:19], v126 offset:45760
	ds_read_b128 v[20:23], v182 offset:27232
	s_waitcnt lgkmcnt(1)
	v_pk_fma_f32 v[98:99], v[98:99], v[16:17], v[24:25]
	v_mfma_f32_32x32x16_bf16 v[0:15], v[60:63], v[178:181], v[0:15]
	v_fma_f32 v100, v100, v18, v26
	v_fma_f32 v101, v101, v19, v27
	v_cvt_pk_bf16_f32 v16, v98, v99
	v_cvt_pk_bf16_f32 v17, v100, v101
	ds_write_b64 v109, v[16:17] offset:27232
	s_waitcnt lgkmcnt(0)
	v_pk_fma_f32 v[102:103], v[102:103], v[196:197], v[28:29]
	v_mfma_f32_32x32x16_bf16 v[0:15], v[56:59], v[20:23], v[0:15]
	v_fma_f32 v104, v104, v198, v30
	v_fma_f32 v105, v105, v199, v31
	v_cvt_pk_bf16_f32 v16, v102, v103
	v_cvt_pk_bf16_f32 v17, v104, v105
	ds_write_b64 v109, v[16:17] offset:27248
	v_add_u32_e32 v16, 0xb600, v131
	s_nop 5
	ds_write2_b32 v16, v0, v1 offset0:64 offset1:196
	v_add_u32_e32 v0, 0xba00, v131
	ds_write2_b32 v0, v2, v3 offset0:72 offset1:204
	ds_write_b32 v132, v4 offset:46848
	v_add_u32_e32 v0, 0xc800, v131
	ds_write2_b32 v0, v5, v6 offset0:100 offset1:232
	ds_write_b32 v131, v7 offset:52656
	ds_write_b32 v133, v8 offset:46848
	v_add_u32_e32 v0, 0xda00, v131
	ds_write2_b32 v0, v9, v10 offset0:4 offset1:136
	ds_write_b32 v131, v11 offset:56880
	ds_write_b32 v134, v12 offset:46848
	v_add_u32_e32 v0, 0xea00, v131
	ds_write2_b32 v0, v13, v14 offset0:36 offset1:168
	ds_write_b32 v131, v15 offset:61104
	s_waitcnt lgkmcnt(0)
	s_barrier
	v_lshl_add_u32 v16, s2, 5, v127
	ds_read_b128 v[0:3], v128 offset:46848
	ds_read_b128 v[4:7], v128 offset:46864
	ds_read_b128 v[8:11], v128 offset:46880
	ds_read_b128 v[12:15], v128 offset:46896
	v_ashrrev_i32_e32 v17, 31, v16
	v_lshl_add_u64 v[16:17], v[16:17], 0, s[12:13]
	v_lshlrev_b64 v[16:17], 10, v[16:17]
	v_lshl_add_u64 v[16:17], v[118:119], 0, v[16:17]
	s_waitcnt lgkmcnt(3)
	v_cvt_pk_bf16_f32 v0, v0, v1
	v_cvt_pk_bf16_f32 v1, v2, v3
	s_waitcnt lgkmcnt(2)
	v_cvt_pk_bf16_f32 v2, v4, v5
	v_cvt_pk_bf16_f32 v3, v6, v7
	global_store_dwordx4 v[16:17], v[0:3], off
	s_waitcnt lgkmcnt(1)
	s_nop 0
	v_cvt_pk_bf16_f32 v0, v8, v9
	v_cvt_pk_bf16_f32 v1, v10, v11
	s_waitcnt lgkmcnt(0)
	v_cvt_pk_bf16_f32 v2, v12, v13
	v_cvt_pk_bf16_f32 v3, v14, v15
	global_store_dwordx4 v[16:17], v[0:3], off offset:16
	s_cbranch_scc1 .LBB0_643
